# early pass: p->bf16 conversion issues its nine loads per thread up front (was one dependent round trip per iteration)
# speedup vs baseline: 1.0015x; 1.0005x over previous
.LBB0_185:
	s_cmp_eq_u32 s99, 0
	s_cbranch_scc1 .Lp0_skip_p
	s_waitcnt lgkmcnt(0)
	s_load_dwordx4 s[4:7], s[18:19], 0x10
	s_add_u32 s10, s16, 0xb800000
	s_addc_u32 s11, s17, 0
	v_lshlrev_b32_e32 v2, 4, v244
	v_lshlrev_b32_e32 v3, 3, v244
	s_lshl_b32 s12, s2, 9
	s_lshl_b32 s13, s85, 6
	s_add_i32 s12, s12, s13
	s_movk_i32 s17, 0x7fff
	s_mov_b32 s18, 0xffff0000
	s_waitcnt lgkmcnt(0)
	s_add_i32 s20, s12, 0x0
	s_cmp_ge_u32 s20, 0x90000
	s_cselect_b32 s21, 0x90000, 0
	s_cselect_b32 s22, 0x800000, 0
	s_cselect_b32 s23, 0x100000, 0
	s_cselect_b32 s36, 0x480000, 0
	s_sub_u32 s20, s20, s21
	s_lshl_b32 s25, s20, 4
	s_add_u32 s22, s22, s25
	s_add_u32 s23, s23, s25
	s_sub_u32 s23, s23, 0x800000
	s_lshl_b32 s26, s20, 3
	s_add_u32 s36, s36, s26
	s_cmp_lt_u32 s20, 0x80000
	s_cselect_b64 s[28:29], s[4:5], s[6:7]
	s_cselect_b32 s22, s22, s23
	s_add_u32 s28, s28, s22
	s_addc_u32 s29, s29, 0
	global_load_dwordx4 v[10:13], v2, s[28:29]
	s_add_i32 s20, s12, 0x20000
	s_cmp_ge_u32 s20, 0x90000
	s_cselect_b32 s21, 0x90000, 0
	s_cselect_b32 s22, 0x800000, 0
	s_cselect_b32 s23, 0x100000, 0
	s_cselect_b32 s37, 0x480000, 0
	s_sub_u32 s20, s20, s21
	s_lshl_b32 s25, s20, 4
	s_add_u32 s22, s22, s25
	s_add_u32 s23, s23, s25
	s_sub_u32 s23, s23, 0x800000
	s_lshl_b32 s26, s20, 3
	s_add_u32 s37, s37, s26
	s_cmp_lt_u32 s20, 0x80000
	s_cselect_b64 s[28:29], s[4:5], s[6:7]
	s_cselect_b32 s22, s22, s23
	s_add_u32 s28, s28, s22
	s_addc_u32 s29, s29, 0
	global_load_dwordx4 v[14:17], v2, s[28:29]
	s_add_i32 s20, s12, 0x40000
	s_cmp_ge_u32 s20, 0x90000
	s_cselect_b32 s21, 0x90000, 0
	s_cselect_b32 s22, 0x800000, 0
	s_cselect_b32 s23, 0x100000, 0
	s_cselect_b32 s38, 0x480000, 0
	s_sub_u32 s20, s20, s21
	s_lshl_b32 s25, s20, 4
	s_add_u32 s22, s22, s25
	s_add_u32 s23, s23, s25
	s_sub_u32 s23, s23, 0x800000
	s_lshl_b32 s26, s20, 3
	s_add_u32 s38, s38, s26
	s_cmp_lt_u32 s20, 0x80000
	s_cselect_b64 s[28:29], s[4:5], s[6:7]
	s_cselect_b32 s22, s22, s23
	s_add_u32 s28, s28, s22
	s_addc_u32 s29, s29, 0
	global_load_dwordx4 v[18:21], v2, s[28:29]
	s_add_i32 s20, s12, 0x60000
	s_cmp_ge_u32 s20, 0x90000
	s_cselect_b32 s21, 0x90000, 0
	s_cselect_b32 s22, 0x800000, 0
	s_cselect_b32 s23, 0x100000, 0
	s_cselect_b32 s39, 0x480000, 0
	s_sub_u32 s20, s20, s21
	s_lshl_b32 s25, s20, 4
	s_add_u32 s22, s22, s25
	s_add_u32 s23, s23, s25
	s_sub_u32 s23, s23, 0x800000
	s_lshl_b32 s26, s20, 3
	s_add_u32 s39, s39, s26
	s_cmp_lt_u32 s20, 0x80000
	s_cselect_b64 s[28:29], s[4:5], s[6:7]
	s_cselect_b32 s22, s22, s23
	s_add_u32 s28, s28, s22
	s_addc_u32 s29, s29, 0
	global_load_dwordx4 v[22:25], v2, s[28:29]
	s_add_i32 s20, s12, 0x80000
	s_cmp_ge_u32 s20, 0x90000
	s_cselect_b32 s21, 0x90000, 0
	s_cselect_b32 s22, 0x800000, 0
	s_cselect_b32 s23, 0x100000, 0
	s_cselect_b32 s40, 0x480000, 0
	s_sub_u32 s20, s20, s21
	s_lshl_b32 s25, s20, 4
	s_add_u32 s22, s22, s25
	s_add_u32 s23, s23, s25
	s_sub_u32 s23, s23, 0x800000
	s_lshl_b32 s26, s20, 3
	s_add_u32 s40, s40, s26
	s_cmp_lt_u32 s20, 0x80000
	s_cselect_b64 s[28:29], s[4:5], s[6:7]
	s_cselect_b32 s22, s22, s23
	s_add_u32 s28, s28, s22
	s_addc_u32 s29, s29, 0
	global_load_dwordx4 v[26:29], v2, s[28:29]
	s_add_i32 s20, s12, 0xa0000
	s_cmp_ge_u32 s20, 0x90000
	s_cselect_b32 s21, 0x90000, 0
	s_cselect_b32 s22, 0x800000, 0
	s_cselect_b32 s23, 0x100000, 0
	s_cselect_b32 s41, 0x480000, 0
	s_sub_u32 s20, s20, s21
	s_lshl_b32 s25, s20, 4
	s_add_u32 s22, s22, s25
	s_add_u32 s23, s23, s25
	s_sub_u32 s23, s23, 0x800000
	s_lshl_b32 s26, s20, 3
	s_add_u32 s41, s41, s26
	s_cmp_lt_u32 s20, 0x80000
	s_cselect_b64 s[28:29], s[4:5], s[6:7]
	s_cselect_b32 s22, s22, s23
	s_add_u32 s28, s28, s22
	s_addc_u32 s29, s29, 0
	global_load_dwordx4 v[30:33], v2, s[28:29]
	s_add_i32 s20, s12, 0xc0000
	s_cmp_ge_u32 s20, 0x90000
	s_cselect_b32 s21, 0x90000, 0
	s_cselect_b32 s22, 0x800000, 0
	s_cselect_b32 s23, 0x100000, 0
	s_cselect_b32 s42, 0x480000, 0
	s_sub_u32 s20, s20, s21
	s_lshl_b32 s25, s20, 4
	s_add_u32 s22, s22, s25
	s_add_u32 s23, s23, s25
	s_sub_u32 s23, s23, 0x800000
	s_lshl_b32 s26, s20, 3
	s_add_u32 s42, s42, s26
	s_cmp_lt_u32 s20, 0x80000
	s_cselect_b64 s[28:29], s[4:5], s[6:7]
	s_cselect_b32 s22, s22, s23
	s_add_u32 s28, s28, s22
	s_addc_u32 s29, s29, 0
	global_load_dwordx4 v[34:37], v2, s[28:29]
	s_add_i32 s20, s12, 0xe0000
	s_cmp_ge_u32 s20, 0x90000
	s_cselect_b32 s21, 0x90000, 0
	s_cselect_b32 s22, 0x800000, 0
	s_cselect_b32 s23, 0x100000, 0
	s_cselect_b32 s43, 0x480000, 0
	s_sub_u32 s20, s20, s21
	s_lshl_b32 s25, s20, 4
	s_add_u32 s22, s22, s25
	s_add_u32 s23, s23, s25
	s_sub_u32 s23, s23, 0x800000
	s_lshl_b32 s26, s20, 3
	s_add_u32 s43, s43, s26
	s_cmp_lt_u32 s20, 0x80000
	s_cselect_b64 s[28:29], s[4:5], s[6:7]
	s_cselect_b32 s22, s22, s23
	s_add_u32 s28, s28, s22
	s_addc_u32 s29, s29, 0
	global_load_dwordx4 v[38:41], v2, s[28:29]
	s_add_i32 s20, s12, 0x100000
	s_cmp_ge_u32 s20, 0x90000
	s_cselect_b32 s21, 0x90000, 0
	s_cselect_b32 s22, 0x800000, 0
	s_cselect_b32 s23, 0x100000, 0
	s_cselect_b32 s44, 0x480000, 0
	s_sub_u32 s20, s20, s21
	s_lshl_b32 s25, s20, 4
	s_add_u32 s22, s22, s25
	s_add_u32 s23, s23, s25
	s_sub_u32 s23, s23, 0x800000
	s_lshl_b32 s26, s20, 3
	s_add_u32 s44, s44, s26
	s_cmp_lt_u32 s20, 0x80000
	s_cselect_b64 s[28:29], s[4:5], s[6:7]
	s_cselect_b32 s22, s22, s23
	s_add_u32 s28, s28, s22
	s_addc_u32 s29, s29, 0
	global_load_dwordx4 v[42:45], v2, s[28:29]
	s_add_u32 s28, s10, s36
	s_addc_u32 s29, s11, 0
	s_waitcnt vmcnt(8)
	v_bfe_u32 v4, v10, 16, 1
	v_bfe_u32 v6, v12, 16, 1
	v_bfe_u32 v5, v11, 16, 1
	v_bfe_u32 v7, v13, 16, 1
	v_add3_u32 v4, v10, v4, s17
	v_add3_u32 v6, v12, v6, s17
	v_add3_u32 v5, v11, v5, s17
	v_add3_u32 v7, v13, v7, s17
	v_lshrrev_b32_e32 v4, 16, v4
	v_lshrrev_b32_e32 v6, 16, v6
	v_and_or_b32 v8, v5, s18, v4
	v_and_or_b32 v9, v7, s18, v6
	global_store_dwordx2 v3, v[8:9], s[28:29]
	s_add_u32 s28, s10, s37
	s_addc_u32 s29, s11, 0
	s_waitcnt vmcnt(8)
	v_bfe_u32 v4, v14, 16, 1
	v_bfe_u32 v6, v16, 16, 1
	v_bfe_u32 v5, v15, 16, 1
	v_bfe_u32 v7, v17, 16, 1
	v_add3_u32 v4, v14, v4, s17
	v_add3_u32 v6, v16, v6, s17
	v_add3_u32 v5, v15, v5, s17
	v_add3_u32 v7, v17, v7, s17
	v_lshrrev_b32_e32 v4, 16, v4
	v_lshrrev_b32_e32 v6, 16, v6
	v_and_or_b32 v8, v5, s18, v4
	v_and_or_b32 v9, v7, s18, v6
	global_store_dwordx2 v3, v[8:9], s[28:29]
	s_add_u32 s28, s10, s38
	s_addc_u32 s29, s11, 0
	s_waitcnt vmcnt(8)
	v_bfe_u32 v4, v18, 16, 1
	v_bfe_u32 v6, v20, 16, 1
	v_bfe_u32 v5, v19, 16, 1
	v_bfe_u32 v7, v21, 16, 1
	v_add3_u32 v4, v18, v4, s17
	v_add3_u32 v6, v20, v6, s17
	v_add3_u32 v5, v19, v5, s17
	v_add3_u32 v7, v21, v7, s17
	v_lshrrev_b32_e32 v4, 16, v4
	v_lshrrev_b32_e32 v6, 16, v6
	v_and_or_b32 v8, v5, s18, v4
	v_and_or_b32 v9, v7, s18, v6
	global_store_dwordx2 v3, v[8:9], s[28:29]
	s_add_u32 s28, s10, s39
	s_addc_u32 s29, s11, 0
	s_waitcnt vmcnt(8)
	v_bfe_u32 v4, v22, 16, 1
	v_bfe_u32 v6, v24, 16, 1
	v_bfe_u32 v5, v23, 16, 1
	v_bfe_u32 v7, v25, 16, 1
	v_add3_u32 v4, v22, v4, s17
	v_add3_u32 v6, v24, v6, s17
	v_add3_u32 v5, v23, v5, s17
	v_add3_u32 v7, v25, v7, s17
	v_lshrrev_b32_e32 v4, 16, v4
	v_lshrrev_b32_e32 v6, 16, v6
	v_and_or_b32 v8, v5, s18, v4
	v_and_or_b32 v9, v7, s18, v6
	global_store_dwordx2 v3, v[8:9], s[28:29]
	s_add_u32 s28, s10, s40
	s_addc_u32 s29, s11, 0
	s_waitcnt vmcnt(8)
	v_bfe_u32 v4, v26, 16, 1
	v_bfe_u32 v6, v28, 16, 1
	v_bfe_u32 v5, v27, 16, 1
	v_bfe_u32 v7, v29, 16, 1
	v_add3_u32 v4, v26, v4, s17
	v_add3_u32 v6, v28, v6, s17
	v_add3_u32 v5, v27, v5, s17
	v_add3_u32 v7, v29, v7, s17
	v_lshrrev_b32_e32 v4, 16, v4
	v_lshrrev_b32_e32 v6, 16, v6
	v_and_or_b32 v8, v5, s18, v4
	v_and_or_b32 v9, v7, s18, v6
	global_store_dwordx2 v3, v[8:9], s[28:29]
	s_add_u32 s28, s10, s41
	s_addc_u32 s29, s11, 0
	s_waitcnt vmcnt(8)
	v_bfe_u32 v4, v30, 16, 1
	v_bfe_u32 v6, v32, 16, 1
	v_bfe_u32 v5, v31, 16, 1
	v_bfe_u32 v7, v33, 16, 1
	v_add3_u32 v4, v30, v4, s17
	v_add3_u32 v6, v32, v6, s17
	v_add3_u32 v5, v31, v5, s17
	v_add3_u32 v7, v33, v7, s17
	v_lshrrev_b32_e32 v4, 16, v4
	v_lshrrev_b32_e32 v6, 16, v6
	v_and_or_b32 v8, v5, s18, v4
	v_and_or_b32 v9, v7, s18, v6
	global_store_dwordx2 v3, v[8:9], s[28:29]
	s_add_u32 s28, s10, s42
	s_addc_u32 s29, s11, 0
	s_waitcnt vmcnt(8)
	v_bfe_u32 v4, v34, 16, 1
	v_bfe_u32 v6, v36, 16, 1
	v_bfe_u32 v5, v35, 16, 1
	v_bfe_u32 v7, v37, 16, 1
	v_add3_u32 v4, v34, v4, s17
	v_add3_u32 v6, v36, v6, s17
	v_add3_u32 v5, v35, v5, s17
	v_add3_u32 v7, v37, v7, s17
	v_lshrrev_b32_e32 v4, 16, v4
	v_lshrrev_b32_e32 v6, 16, v6
	v_and_or_b32 v8, v5, s18, v4
	v_and_or_b32 v9, v7, s18, v6
	global_store_dwordx2 v3, v[8:9], s[28:29]
	s_add_u32 s28, s10, s43
	s_addc_u32 s29, s11, 0
	s_waitcnt vmcnt(8)
	v_bfe_u32 v4, v38, 16, 1
	v_bfe_u32 v6, v40, 16, 1
	v_bfe_u32 v5, v39, 16, 1
	v_bfe_u32 v7, v41, 16, 1
	v_add3_u32 v4, v38, v4, s17
	v_add3_u32 v6, v40, v6, s17
	v_add3_u32 v5, v39, v5, s17
	v_add3_u32 v7, v41, v7, s17
	v_lshrrev_b32_e32 v4, 16, v4
	v_lshrrev_b32_e32 v6, 16, v6
	v_and_or_b32 v8, v5, s18, v4
	v_and_or_b32 v9, v7, s18, v6
	global_store_dwordx2 v3, v[8:9], s[28:29]
	s_add_u32 s28, s10, s44
	s_addc_u32 s29, s11, 0
	s_waitcnt vmcnt(8)
	v_bfe_u32 v4, v42, 16, 1
	v_bfe_u32 v6, v44, 16, 1
	v_bfe_u32 v5, v43, 16, 1
	v_bfe_u32 v7, v45, 16, 1
	v_add3_u32 v4, v42, v4, s17
	v_add3_u32 v6, v44, v6, s17
	v_add3_u32 v5, v43, v5, s17
	v_add3_u32 v7, v45, v7, s17
	v_lshrrev_b32_e32 v4, 16, v4
	v_lshrrev_b32_e32 v6, 16, v6
	v_and_or_b32 v8, v5, s18, v4
	v_and_or_b32 v9, v7, s18, v6
	global_store_dwordx2 v3, v[8:9], s[28:29]
	s_branch .Lp0_skip_p
